# MODE0 attention tile: shorter near/far dispatch on the far path, bias index math only on near tiles
# speedup vs baseline: 1.0122x; 1.0013x over previous
; #define LAS __attribute__((address_space(3)))
; template <int MODE>
; __device__ __forceinline__ void attn_unit(LAS unsigned char* lds, const Ptrs& P, int nq, int nt_block, int qpos0, bool sample, int h,
;                                           const float* relb  , const float* lamp, const float* subg, bf16_t* Obase  , int wv) {
;     ...
;                 const int k0 = t * 64;
;                 const bool farT = (k0 + 63 - qmin <= -91);
;                 const int ib = k0 - qposl + 192 + 4 * hi;
;                 bf16x8 pa[4], pb[4];
;                 bf16x8 kf[4], kg2[4];
; #pragma unroll
;                 for (int ks = 0; ks < 2; ++ks) { kf[2 * ks] = *(const LAS bf16x8*)(kb + ks * 2048); kf[2 * ks + 1] = *(const LAS bf16x8*)(kb + ks * 2048 + 512); }
;                 {
;                     f32x16 p0, p1;
;                     if (farT) {
;                         p0 = __builtin_amdgcn_mfma_f32_32x32x16_bf16(kf[0], qf[0], ng1, 0, 0, 0);
;                         p1 = __builtin_amdgcn_mfma_f32_32x32x16_bf16(kf[1], qf[0], ng1, 0, 0, 0);
;                     } else {
;                         const float nb = ng1[0] - cbias;
; #pragma unroll
;                         for (int r = 0; r < 16; ++r) { const int idx = ib + (r & 3) + 8 * (r >> 2); p0[r] = bt[idx] + nb; p1[r] = bt[idx + 32] + nb; }
;                         p0 = __builtin_amdgcn_mfma_f32_32x32x16_bf16(kf[0], qf[0], p0, 0, 0, 0);
;                         p1 = __builtin_amdgcn_mfma_f32_32x32x16_bf16(kf[1], qf[0], p1, 0, 0, 0);
;                     }
.LBB0_1226:
	s_or_b32 s28, s24, s41
	s_cmp_ge_i32 s15, s28
	s_cselect_b64 s[2:3], -1, 0
	s_and_b64 s[2:3], s[38:39], s[2:3]
	s_andn2_b64 vcc, exec, s[2:3]
	s_cbranch_vccnz .LBB0_1225
	s_mul_i32 s2, s24, 0x5000
	s_add_i32 s42, s37, s2
	v_add_u32_e32 v4, s42, v228
	v_add_u32_e32 v4, v4, v229
	ds_read_b128 v[76:79], v4
	ds_read_b128 v[80:83], v4 offset:512
	ds_read_b128 v[72:75], v4 offset:2048
	ds_read_b128 v[150:153], v4 offset:2560
	s_lshl_b32 s2, s28, 6
	s_sub_i32 s3, s2, s8
	s_cmpk_gt_i32 s3, 0xff66
	s_cselect_b64 s[26:27], -1, 0
	s_mov_b64 s[2:3], -1
	s_and_b64 vcc, exec, s[26:27]
	s_cbranch_vccz .Lm0p_far1
	s_lshl_b32 s2, s28, 6
	v_add_u32_e32 v84, s2, v232
	v_lshl_add_u32 v84, v84, 2, 0
	v_add_u32_e32 v85, 0x14000, v84
	ds_read2_b32 v[118:119], v85 offset1:1
	ds_read2_b32 v[120:121], v85 offset0:2 offset1:3
	ds_read2_b32 v[122:123], v85 offset0:8 offset1:9
	ds_read2_b32 v[124:125], v85 offset0:10 offset1:11
	ds_read2_b32 v[126:127], v85 offset0:16 offset1:17
	ds_read2_b32 v[128:129], v85 offset0:18 offset1:19
	ds_read2_b32 v[130:131], v85 offset0:24 offset1:25
	ds_read2_b32 v[132:133], v85 offset0:26 offset1:27
	ds_read2_b32 v[154:155], v85 offset0:32 offset1:33
	ds_read2_b32 v[136:137], v85 offset0:34 offset1:35
	ds_read2_b32 v[138:139], v85 offset0:40 offset1:41
	ds_read2_b32 v[140:141], v85 offset0:42 offset1:43
	ds_read2_b32 v[142:143], v85 offset0:48 offset1:49
	ds_read2_b32 v[144:145], v85 offset0:50 offset1:51
	ds_read2_b32 v[146:147], v85 offset0:56 offset1:57
	ds_read2_b32 v[148:149], v85 offset0:58 offset1:59
	v_sub_f32_e32 v134, v102, v70
	s_waitcnt lgkmcnt(8)
	v_pk_add_f32 v[132:133], v[134:135], v[132:133] op_sel_hi:[0,1]
	v_pk_add_f32 v[130:131], v[134:135], v[130:131] op_sel_hi:[0,1]
	v_pk_add_f32 v[128:129], v[134:135], v[128:129] op_sel_hi:[0,1]
	v_pk_add_f32 v[126:127], v[134:135], v[126:127] op_sel_hi:[0,1]
	v_pk_add_f32 v[124:125], v[134:135], v[124:125] op_sel_hi:[0,1]
	v_pk_add_f32 v[122:123], v[134:135], v[122:123] op_sel_hi:[0,1]
	v_pk_add_f32 v[120:121], v[134:135], v[120:121] op_sel_hi:[0,1]
	v_pk_add_f32 v[118:119], v[134:135], v[118:119] op_sel_hi:[0,1]
	s_waitcnt lgkmcnt(0)
	v_pk_add_f32 v[148:149], v[134:135], v[148:149] op_sel_hi:[0,1]
	v_pk_add_f32 v[146:147], v[134:135], v[146:147] op_sel_hi:[0,1]
	v_pk_add_f32 v[144:145], v[134:135], v[144:145] op_sel_hi:[0,1]
	v_pk_add_f32 v[142:143], v[134:135], v[142:143] op_sel_hi:[0,1]
	v_pk_add_f32 v[140:141], v[134:135], v[140:141] op_sel_hi:[0,1]
	v_pk_add_f32 v[138:139], v[134:135], v[138:139] op_sel_hi:[0,1]
	v_pk_add_f32 v[136:137], v[134:135], v[136:137] op_sel_hi:[0,1]
	v_pk_add_f32 v[134:135], v[134:135], v[154:155] op_sel_hi:[0,1]
	v_mfma_f32_32x32x16_bf16 v[118:133], v[76:79], v[0:3], v[118:133]
	s_mov_b64 s[2:3], 0
	v_mfma_f32_32x32x16_bf16 v[134:149], v[80:83], v[0:3], v[134:149]

; template <int MODE>
; __device__ __forceinline__ void attn_unit(LAS unsigned char* lds, const Ptrs& P, int nq, int nt_block, int qpos0, bool sample, int h,
;                                           const float* relb  , const float* lamp, const float* subg, bf16_t* Obase  , int wv) {
;     ...
;                     if (farT) {
;                         p0 = __builtin_amdgcn_mfma_f32_32x32x16_bf16(kf[0], qf[0], ng1, 0, 0, 0);
;                         p1 = __builtin_amdgcn_mfma_f32_32x32x16_bf16(kf[1], qf[0], ng1, 0, 0, 0);
;                     } else {
.Lm0p_far1:
	s_waitcnt lgkmcnt(3)
	v_mfma_f32_32x32x16_bf16 v[118:133], v[76:79], v[0:3], v[102:117]
	s_waitcnt lgkmcnt(2)
	v_mfma_f32_32x32x16_bf16 v[134:149], v[80:83], v[0:3], v[102:117]

; template <int MODE>
; __device__ __forceinline__ void attn_unit(LAS unsigned char* lds, const Ptrs& P, int nq, int nt_block, int qpos0, bool sample, int h,
;                                           const float* relb  , const float* lamp, const float* subg, bf16_t* Obase  , int wv) {
;     ...
;                     if (farT) {
;                         s0 = __builtin_amdgcn_mfma_f32_32x32x16_bf16(kg2[0], qf[2], ng2, 0, 0, 0);
;                         s1 = __builtin_amdgcn_mfma_f32_32x32x16_bf16(kg2[1], qf[2], ng2, 0, 0, 0);
;                     } else {
;                         const float nb = ng2[0] - cbias;
; #pragma unroll
;                         for (int r = 0; r < 16; ++r) { const int idx = ib + (r & 3) + 8 * (r >> 2); s0[r] = bt[idx] + nb; s1[r] = bt[idx + 32] + nb; }
;                         s0 = __builtin_amdgcn_mfma_f32_32x32x16_bf16(kg2[0], qf[2], s0, 0, 0, 0);
;                         s1 = __builtin_amdgcn_mfma_f32_32x32x16_bf16(kg2[1], qf[2], s1, 0, 0, 0);
;                     }
.LBB0_1239:
	s_mov_b64 s[28:29], -1
	s_and_b64 vcc, exec, s[2:3]
	s_cmp_lg_u64 s[26:27], 0
	s_cbranch_scc0 .Lqk2h_done_p
	v_add_u32_e32 v164, 0x14000, v84
	v_sub_f32_e32 v4, v86, v70
	ds_read2_b32 v[84:85], v164 offset1:1
	ds_read2_b32 v[150:151], v164 offset0:2 offset1:3
	ds_read2_b32 v[152:153], v164 offset0:8 offset1:9
	ds_read2_b32 v[154:155], v164 offset0:10 offset1:11
	ds_read2_b32 v[156:157], v164 offset0:16 offset1:17
	ds_read2_b32 v[158:159], v164 offset0:18 offset1:19
	ds_read2_b32 v[160:161], v164 offset0:24 offset1:25
	ds_read2_b32 v[162:163], v164 offset0:26 offset1:27
	ds_read2_b32 v[236:237], v164 offset0:32 offset1:33
	ds_read2_b32 v[238:239], v164 offset0:34 offset1:35
	ds_read2_b32 v[240:241], v164 offset0:40 offset1:41
	ds_read2_b32 v[242:243], v164 offset0:42 offset1:43
	s_waitcnt lgkmcnt(4)
	v_pk_add_f32 v[180:181], v[4:5], v[162:163] op_sel_hi:[0,1]
	v_pk_add_f32 v[178:179], v[4:5], v[160:161] op_sel_hi:[0,1]
	v_pk_add_f32 v[176:177], v[4:5], v[158:159] op_sel_hi:[0,1]
	v_pk_add_f32 v[174:175], v[4:5], v[156:157] op_sel_hi:[0,1]
	ds_read2_b32 v[156:157], v164 offset0:48 offset1:49
	ds_read2_b32 v[158:159], v164 offset0:50 offset1:51
	ds_read2_b32 v[160:161], v164 offset0:56 offset1:57
	ds_read2_b32 v[162:163], v164 offset0:58 offset1:59
	v_pk_add_f32 v[172:173], v[4:5], v[154:155] op_sel_hi:[0,1]
	v_pk_add_f32 v[170:171], v[4:5], v[152:153] op_sel_hi:[0,1]
	v_pk_add_f32 v[168:169], v[4:5], v[150:151] op_sel_hi:[0,1]
	v_pk_add_f32 v[166:167], v[4:5], v[84:85] op_sel_hi:[0,1]
	s_waitcnt lgkmcnt(0)
	v_pk_add_f32 v[164:165], v[4:5], v[162:163] op_sel_hi:[0,1]
	v_pk_add_f32 v[162:163], v[4:5], v[160:161] op_sel_hi:[0,1]
	v_pk_add_f32 v[160:161], v[4:5], v[158:159] op_sel_hi:[0,1]
	v_pk_add_f32 v[158:159], v[4:5], v[156:157] op_sel_hi:[0,1]
	v_pk_add_f32 v[156:157], v[4:5], v[242:243] op_sel_hi:[0,1]
	v_pk_add_f32 v[154:155], v[4:5], v[240:241] op_sel_hi:[0,1]
	v_pk_add_f32 v[152:153], v[4:5], v[238:239] op_sel_hi:[0,1]
	v_pk_add_f32 v[150:151], v[4:5], v[236:237] op_sel_hi:[0,1]
	v_mfma_f32_32x32x16_bf16 v[166:181], v[80:83], v[186:189], v[166:181]
	s_nop 0
	v_mfma_f32_32x32x16_bf16 v[150:165], v[210:213], v[186:189], v[150:165]
	s_cbranch_execz .LBB0_1242
	s_branch .LBB0_1243
